# Q up-proj (q_nope tiles) epilogue: the 8 per-row part[r] loads issued up front, one wait
# baseline (speedup 1.0000x reference)
; __device__ __forceinline__ u32x4 pack8(const f32x4 a, const f32x4 b) { u32x4 w; w.x = cvt_pk_bf16(a[0], a[1]); w.y = cvt_pk_bf16(a[2], a[3]); w.z = cvt_pk_bf16(b[0], b[1]); w.w = cvt_pk_bf16(b[2], b[3]); return w; }
; #define EPI_ROWLOOP _Pragma("unroll") for (int ai = 0; ai < 2; ++ai) _Pragma("unroll") for (int m = 0; m < 4; ++m)
;     __device__ __forceinline__ void operator()(const f32x4 (&acc)[2][2][4][2], const Unit& u, int wr, int wc, int fr, int fq) const {
;     ...
;         if (pn < 4) {
;             bf16_t* QN = (bf16_t*)(ws + WS_R1);
;             EPI_ROWLOOP { const int r = row0 + ai * HALF + m * 16; const f32x4 pq = part[r]; const float rs = __builtin_amdgcn_rsqf(((pq[0] + pq[1]) + (pq[2] + pq[3])) * (1.0f / 256.0f) + EP_EPS) * qscale;
;                 bf16_t* rowp = QN + (size_t)r * 1024 + pn * 256 + cl;
; #pragma unroll
;                 for (int bj = 0; bj < 2; ++bj) *(u32x4*)(rowp + bj * HALF) = pack8(acc[ai][bj][m][0] * rs, acc[ai][bj][m][1] * rs); }
.LBB0_574:
	v_lshl_add_u64 v[128:129], v[156:157], 4, s[50:51]
	global_load_dwordx4 v[202:205], v[128:129], off
	global_load_dwordx4 v[206:209], v[128:129], off offset:256
	global_load_dwordx4 v[210:213], v[128:129], off offset:512
	global_load_dwordx4 v[214:217], v[128:129], off offset:768
	global_load_dwordx4 v[218:221], v[128:129], off offset:2048
	global_load_dwordx4 v[222:225], v[128:129], off offset:2304
	global_load_dwordx4 v[226:229], v[128:129], off offset:2560
	global_load_dwordx4 v[230:233], v[128:129], off offset:2816
	s_ashr_i32 s59, s58, 31
	v_lshlrev_b64 v[130:131], 11, v[156:157]
	v_or_b32_e32 v160, 16, v156
	v_lshl_add_u64 v[158:159], s[58:59], 1, v[146:147]
	v_ashrrev_i32_e32 v161, 31, v160
	v_lshl_add_u64 v[130:131], v[158:159], 0, v[130:131]
	s_mov_b32 s12, 0x40000
	s_mov_b64 s[58:59], 0x40000
	s_waitcnt vmcnt(0)
	v_mov_b32_e32 v170, v202
	v_mov_b32_e32 v171, v203
	v_mov_b32_e32 v172, v204
	v_mov_b32_e32 v173, v205
	v_mov_b32_e32 v162, v171
	v_mov_b32_e32 v163, v172
	v_mov_b32_e32 v171, v173
	v_pk_add_f32 v[162:163], v[162:163], v[170:171]
	s_nop 0
	v_add_f32_e32 v140, v162, v163
	v_fmamk_f32 v140, v140, 0x3b800000, v169
	v_rsq_f32_e32 v140, v140
	v_lshl_add_u64 v[162:163], v[160:161], 4, s[50:51]
	v_mul_f32_e32 v140, 0x3dd53b94, v140
	v_pk_mul_f32 v[122:123], v[122:123], v[140:141] op_sel_hi:[1,0]
	v_pk_mul_f32 v[120:121], v[120:121], v[140:141] op_sel_hi:[1,0]
	v_pk_mul_f32 v[126:127], v[126:127], v[140:141] op_sel_hi:[1,0]
	v_pk_mul_f32 v[124:125], v[124:125], v[140:141] op_sel_hi:[1,0]
	v_pk_mul_f32 v[118:119], v[118:119], v[140:141] op_sel_hi:[1,0]
	v_pk_mul_f32 v[116:117], v[116:117], v[140:141] op_sel_hi:[1,0]
	v_pk_mul_f32 v[170:171], v[114:115], v[140:141] op_sel_hi:[1,0]
	v_pk_mul_f32 v[172:173], v[112:113], v[140:141] op_sel_hi:[1,0]
	v_cvt_pk_bf16_f32 v112, v120, v121
	v_cvt_pk_bf16_f32 v113, v122, v123
	v_cvt_pk_bf16_f32 v114, v124, v125
	v_cvt_pk_bf16_f32 v115, v126, v127
	v_cvt_pk_bf16_f32 v116, v116, v117
	v_cvt_pk_bf16_f32 v117, v118, v119
	v_cvt_pk_bf16_f32 v118, v172, v173
	v_cvt_pk_bf16_f32 v119, v170, v171
	global_store_dwordx4 v[130:131], v[112:115], off
	global_store_dwordx4 v[130:131], v[116:119], off offset:256
	s_nop 1
	v_or_b32_e32 v112, 32, v156
	v_ashrrev_i32_e32 v113, 31, v112
	v_mov_b32_e32 v114, v206
	v_mov_b32_e32 v115, v207
	v_mov_b32_e32 v116, v208
	v_mov_b32_e32 v117, v209
	v_mov_b32_e32 v118, v115
	v_mov_b32_e32 v119, v116
	v_mov_b32_e32 v115, v117
	v_pk_add_f32 v[114:115], v[118:119], v[114:115]
	v_lshl_add_u64 v[116:117], v[112:113], 4, s[50:51]
	v_add_f32_e32 v114, v114, v115
	v_fmamk_f32 v114, v114, 0x3b800000, v169
	v_rsq_f32_e32 v118, v114
	v_lshlrev_b64 v[114:115], 11, v[160:161]
	v_lshl_add_u64 v[114:115], v[158:159], 0, v[114:115]
	v_mul_f32_e32 v118, 0x3dd53b94, v118
	v_pk_mul_f32 v[110:111], v[110:111], v[118:119] op_sel_hi:[1,0]
	v_pk_mul_f32 v[108:109], v[108:109], v[118:119] op_sel_hi:[1,0]
	v_pk_mul_f32 v[106:107], v[106:107], v[118:119] op_sel_hi:[1,0]
	v_pk_mul_f32 v[104:105], v[104:105], v[118:119] op_sel_hi:[1,0]
	v_pk_mul_f32 v[102:103], v[102:103], v[118:119] op_sel_hi:[1,0]
	v_pk_mul_f32 v[100:101], v[100:101], v[118:119] op_sel_hi:[1,0]
	v_pk_mul_f32 v[120:121], v[98:99], v[118:119] op_sel_hi:[1,0]
	v_pk_mul_f32 v[118:119], v[96:97], v[118:119] op_sel_hi:[1,0]
	v_cvt_pk_bf16_f32 v96, v108, v109
	v_cvt_pk_bf16_f32 v97, v110, v111
	v_cvt_pk_bf16_f32 v98, v104, v105
	v_cvt_pk_bf16_f32 v99, v106, v107
	v_cvt_pk_bf16_f32 v100, v100, v101
	v_cvt_pk_bf16_f32 v101, v102, v103
	v_cvt_pk_bf16_f32 v102, v118, v119
	v_cvt_pk_bf16_f32 v103, v120, v121
	global_store_dwordx4 v[114:115], v[96:99], off
	global_store_dwordx4 v[114:115], v[100:103], off offset:256
	s_nop 1
	s_nop 0
	v_or_b32_e32 v100, 48, v156
	v_ashrrev_i32_e32 v101, 31, v100
	v_mov_b32_e32 v96, v210
	v_mov_b32_e32 v97, v211
	v_mov_b32_e32 v98, v212
	v_mov_b32_e32 v99, v213
	v_mov_b32_e32 v102, v97
	v_mov_b32_e32 v103, v98
	v_mov_b32_e32 v97, v99
	v_pk_add_f32 v[96:97], v[102:103], v[96:97]
	v_lshl_add_u64 v[98:99], v[100:101], 4, s[50:51]
	v_add_f32_e32 v96, v96, v97
	v_fmamk_f32 v96, v96, 0x3b800000, v169
	v_rsq_f32_e32 v102, v96
	v_lshlrev_b64 v[96:97], 11, v[112:113]
	v_lshl_add_u64 v[96:97], v[158:159], 0, v[96:97]
	v_mul_f32_e32 v102, 0x3dd53b94, v102
	v_pk_mul_f32 v[94:95], v[94:95], v[102:103] op_sel_hi:[1,0]
	v_pk_mul_f32 v[92:93], v[92:93], v[102:103] op_sel_hi:[1,0]
	v_pk_mul_f32 v[90:91], v[90:91], v[102:103] op_sel_hi:[1,0]
	v_pk_mul_f32 v[88:89], v[88:89], v[102:103] op_sel_hi:[1,0]
	v_pk_mul_f32 v[86:87], v[86:87], v[102:103] op_sel_hi:[1,0]
	v_pk_mul_f32 v[84:85], v[84:85], v[102:103] op_sel_hi:[1,0]
	v_pk_mul_f32 v[104:105], v[82:83], v[102:103] op_sel_hi:[1,0]
	v_pk_mul_f32 v[102:103], v[80:81], v[102:103] op_sel_hi:[1,0]
	v_cvt_pk_bf16_f32 v80, v92, v93
	v_cvt_pk_bf16_f32 v81, v94, v95
	v_cvt_pk_bf16_f32 v82, v88, v89
	v_cvt_pk_bf16_f32 v83, v90, v91
	v_cvt_pk_bf16_f32 v84, v84, v85
	v_cvt_pk_bf16_f32 v85, v86, v87
	v_cvt_pk_bf16_f32 v86, v102, v103
	v_cvt_pk_bf16_f32 v87, v104, v105
	global_store_dwordx4 v[96:97], v[80:83], off
	global_store_dwordx4 v[96:97], v[84:87], off offset:256
	s_nop 1
	v_mov_b32_e32 v80, v214
	v_mov_b32_e32 v81, v215
	v_mov_b32_e32 v82, v216
	v_mov_b32_e32 v83, v217
	v_mov_b32_e32 v84, v81
	v_mov_b32_e32 v85, v82
	v_mov_b32_e32 v81, v83
	v_pk_add_f32 v[80:81], v[84:85], v[80:81]
	s_nop 0
	v_add_f32_e32 v80, v80, v81
	v_fmamk_f32 v80, v80, 0x3b800000, v169
	v_rsq_f32_e32 v82, v80
	v_lshlrev_b64 v[80:81], 11, v[100:101]
	v_lshl_add_u64 v[80:81], v[158:159], 0, v[80:81]
	v_mul_f32_e32 v82, 0x3dd53b94, v82
	v_pk_mul_f32 v[78:79], v[78:79], v[82:83] op_sel_hi:[1,0]
; __device__ __forceinline__ u32x4 pack8(const f32x4 a, const f32x4 b) { u32x4 w; w.x = cvt_pk_bf16(a[0], a[1]); w.y = cvt_pk_bf16(a[2], a[3]); w.z = cvt_pk_bf16(b[0], b[1]); w.w = cvt_pk_bf16(b[2], b[3]); return w; }
; #define EPI_ROWLOOP _Pragma("unroll") for (int ai = 0; ai < 2; ++ai) _Pragma("unroll") for (int m = 0; m < 4; ++m)
;     __device__ __forceinline__ void operator()(const f32x4 (&acc)[2][2][4][2], const Unit& u, int wr, int wc, int fr, int fq) const {
;     ...
;             EPI_ROWLOOP { const int r = row0 + ai * HALF + m * 16; const f32x4 pq = part[r]; const float rs = __builtin_amdgcn_rsqf(((pq[0] + pq[1]) + (pq[2] + pq[3])) * (1.0f / 256.0f) + EP_EPS) * qscale;
;                 bf16_t* rowp = QN + (size_t)r * 1024 + pn * 256 + cl;
; #pragma unroll
;                 for (int bj = 0; bj < 2; ++bj) *(u32x4*)(rowp + bj * HALF) = pack8(acc[ai][bj][m][0] * rs, acc[ai][bj][m][1] * rs); }
	v_pk_mul_f32 v[76:77], v[76:77], v[82:83] op_sel_hi:[1,0]
	v_pk_mul_f32 v[74:75], v[74:75], v[82:83] op_sel_hi:[1,0]
	v_pk_mul_f32 v[72:73], v[72:73], v[82:83] op_sel_hi:[1,0]
	v_pk_mul_f32 v[70:71], v[70:71], v[82:83] op_sel_hi:[1,0]
	v_pk_mul_f32 v[68:69], v[68:69], v[82:83] op_sel_hi:[1,0]
	v_pk_mul_f32 v[84:85], v[66:67], v[82:83] op_sel_hi:[1,0]
	v_pk_mul_f32 v[82:83], v[64:65], v[82:83] op_sel_hi:[1,0]
	v_cvt_pk_bf16_f32 v64, v76, v77
	v_cvt_pk_bf16_f32 v65, v78, v79
	v_cvt_pk_bf16_f32 v66, v72, v73
	v_cvt_pk_bf16_f32 v67, v74, v75
	v_cvt_pk_bf16_f32 v68, v68, v69
	v_cvt_pk_bf16_f32 v69, v70, v71
	v_cvt_pk_bf16_f32 v70, v82, v83
	v_cvt_pk_bf16_f32 v71, v84, v85
	global_store_dwordx4 v[80:81], v[64:67], off
	global_store_dwordx4 v[80:81], v[68:71], off offset:256
	s_nop 1
	s_nop 0
	v_lshl_add_u64 v[68:69], v[130:131], 0, s[58:59]
	s_mov_b64 s[58:59], 0x48000
	v_mov_b32_e32 v64, v218
	v_mov_b32_e32 v65, v219
	v_mov_b32_e32 v66, v220
	v_mov_b32_e32 v67, v221
	v_mov_b32_e32 v70, v65
	v_mov_b32_e32 v71, v66
	v_mov_b32_e32 v65, v67
	v_pk_add_f32 v[64:65], v[70:71], v[64:65]
	s_nop 0
	v_add_f32_e32 v64, v64, v65
	v_fmamk_f32 v64, v64, 0x3b800000, v169
	v_rsq_f32_e32 v66, v64
	v_add_co_u32_e32 v64, vcc, s12, v130
	v_mul_f32_e32 v66, 0x3dd53b94, v66
	v_pk_mul_f32 v[62:63], v[62:63], v[66:67] op_sel_hi:[1,0]
	v_pk_mul_f32 v[60:61], v[60:61], v[66:67] op_sel_hi:[1,0]
	v_pk_mul_f32 v[58:59], v[58:59], v[66:67] op_sel_hi:[1,0]
	v_pk_mul_f32 v[56:57], v[56:57], v[66:67] op_sel_hi:[1,0]
	v_addc_co_u32_e32 v65, vcc, 0, v131, vcc
	v_pk_mul_f32 v[54:55], v[54:55], v[66:67] op_sel_hi:[1,0]
	v_pk_mul_f32 v[52:53], v[52:53], v[66:67] op_sel_hi:[1,0]
	v_pk_mul_f32 v[70:71], v[50:51], v[66:67] op_sel_hi:[1,0]
	v_pk_mul_f32 v[66:67], v[48:49], v[66:67] op_sel_hi:[1,0]
	v_cvt_pk_bf16_f32 v48, v60, v61
	v_cvt_pk_bf16_f32 v49, v62, v63
	v_cvt_pk_bf16_f32 v50, v56, v57
	v_cvt_pk_bf16_f32 v51, v58, v59
	v_cvt_pk_bf16_f32 v52, v52, v53
	v_cvt_pk_bf16_f32 v53, v54, v55
	v_cvt_pk_bf16_f32 v54, v66, v67
	v_cvt_pk_bf16_f32 v55, v70, v71
	global_store_dwordx4 v[64:65], v[48:51], off
	global_store_dwordx4 v[68:69], v[52:55], off offset:256
	s_nop 1
	s_nop 0
	v_lshl_add_u64 v[52:53], v[130:131], 0, s[58:59]
	v_mov_b32_e32 v48, v222
	v_mov_b32_e32 v49, v223
	v_mov_b32_e32 v50, v224
	v_mov_b32_e32 v51, v225
	v_mov_b32_e32 v54, v49
	v_mov_b32_e32 v55, v50
	v_mov_b32_e32 v49, v51
	v_pk_add_f32 v[48:49], v[54:55], v[48:49]
	s_nop 0
	v_add_f32_e32 v48, v48, v49
	v_fmamk_f32 v48, v48, 0x3b800000, v169
	v_rsq_f32_e32 v50, v48
	v_add_co_u32_e32 v48, vcc, s85, v130
	v_mul_f32_e32 v50, 0x3dd53b94, v50
	v_pk_mul_f32 v[46:47], v[46:47], v[50:51] op_sel_hi:[1,0]
	v_pk_mul_f32 v[44:45], v[44:45], v[50:51] op_sel_hi:[1,0]
	v_pk_mul_f32 v[42:43], v[42:43], v[50:51] op_sel_hi:[1,0]
	v_pk_mul_f32 v[40:41], v[40:41], v[50:51] op_sel_hi:[1,0]
	v_addc_co_u32_e32 v49, vcc, 0, v131, vcc
	v_pk_mul_f32 v[38:39], v[38:39], v[50:51] op_sel_hi:[1,0]
	v_pk_mul_f32 v[36:37], v[36:37], v[50:51] op_sel_hi:[1,0]
	v_pk_mul_f32 v[54:55], v[34:35], v[50:51] op_sel_hi:[1,0]
	v_pk_mul_f32 v[50:51], v[32:33], v[50:51] op_sel_hi:[1,0]
	v_cvt_pk_bf16_f32 v32, v44, v45
	v_cvt_pk_bf16_f32 v33, v46, v47
	v_cvt_pk_bf16_f32 v34, v40, v41
	v_cvt_pk_bf16_f32 v35, v42, v43
	v_cvt_pk_bf16_f32 v36, v36, v37
	v_cvt_pk_bf16_f32 v37, v38, v39
	v_cvt_pk_bf16_f32 v38, v50, v51
	v_cvt_pk_bf16_f32 v39, v54, v55
	global_store_dwordx4 v[48:49], v[32:35], off
	global_store_dwordx4 v[52:53], v[36:39], off offset:256
	s_nop 1
	s_nop 0
	v_lshl_add_u64 v[36:37], v[130:131], 0, s[52:53]
	v_mov_b32_e32 v32, v226
	v_mov_b32_e32 v33, v227
	v_mov_b32_e32 v34, v228
	v_mov_b32_e32 v35, v229
	v_mov_b32_e32 v38, v33
	v_mov_b32_e32 v39, v34
	v_mov_b32_e32 v33, v35
	v_pk_add_f32 v[32:33], v[38:39], v[32:33]
	s_nop 0
	v_add_f32_e32 v32, v32, v33
	v_fmamk_f32 v32, v32, 0x3b800000, v169
	v_rsq_f32_e32 v34, v32
	v_add_co_u32_e32 v32, vcc, s86, v130
	v_mul_f32_e32 v34, 0x3dd53b94, v34
	v_pk_mul_f32 v[30:31], v[30:31], v[34:35] op_sel_hi:[1,0]
	v_pk_mul_f32 v[28:29], v[28:29], v[34:35] op_sel_hi:[1,0]
	v_pk_mul_f32 v[26:27], v[26:27], v[34:35] op_sel_hi:[1,0]
	v_pk_mul_f32 v[24:25], v[24:25], v[34:35] op_sel_hi:[1,0]
	v_addc_co_u32_e32 v33, vcc, 0, v131, vcc
	v_pk_mul_f32 v[22:23], v[22:23], v[34:35] op_sel_hi:[1,0]
	v_pk_mul_f32 v[20:21], v[20:21], v[34:35] op_sel_hi:[1,0]
	v_pk_mul_f32 v[38:39], v[18:19], v[34:35] op_sel_hi:[1,0]
	v_pk_mul_f32 v[34:35], v[16:17], v[34:35] op_sel_hi:[1,0]
	v_cvt_pk_bf16_f32 v16, v28, v29
	v_cvt_pk_bf16_f32 v17, v30, v31
	v_cvt_pk_bf16_f32 v18, v24, v25
	v_cvt_pk_bf16_f32 v19, v26, v27
	v_cvt_pk_bf16_f32 v20, v20, v21
	v_cvt_pk_bf16_f32 v21, v22, v23
	v_cvt_pk_bf16_f32 v22, v34, v35
	v_cvt_pk_bf16_f32 v23, v38, v39
	global_store_dwordx4 v[32:33], v[16:19], off
	global_store_dwordx4 v[36:37], v[20:23], off offset:256
	s_nop 1
	s_nop 0
	v_lshl_add_u64 v[20:21], v[130:131], 0, s[54:55]
	v_mov_b32_e32 v16, v230
	v_mov_b32_e32 v17, v231
	v_mov_b32_e32 v18, v232
	v_mov_b32_e32 v19, v233
	v_mov_b32_e32 v22, v17
	v_mov_b32_e32 v23, v18
	v_mov_b32_e32 v17, v19
	v_pk_add_f32 v[16:17], v[22:23], v[16:17]
	s_nop 0
	v_add_f32_e32 v16, v16, v17
	v_fmamk_f32 v16, v16, 0x3b800000, v169
	v_rsq_f32_e32 v18, v16
	v_add_co_u32_e32 v16, vcc, s90, v130
	v_mul_f32_e32 v18, 0x3dd53b94, v18
	v_pk_mul_f32 v[14:15], v[14:15], v[18:19] op_sel_hi:[1,0]
	v_pk_mul_f32 v[12:13], v[12:13], v[18:19] op_sel_hi:[1,0]
	v_pk_mul_f32 v[10:11], v[10:11], v[18:19] op_sel_hi:[1,0]
	v_pk_mul_f32 v[8:9], v[8:9], v[18:19] op_sel_hi:[1,0]
	v_addc_co_u32_e32 v17, vcc, 0, v131, vcc
	v_pk_mul_f32 v[6:7], v[6:7], v[18:19] op_sel_hi:[1,0]
	v_pk_mul_f32 v[4:5], v[4:5], v[18:19] op_sel_hi:[1,0]
	v_pk_mul_f32 v[22:23], v[2:3], v[18:19] op_sel_hi:[1,0]
	v_pk_mul_f32 v[18:19], v[0:1], v[18:19] op_sel_hi:[1,0]
	v_cvt_pk_bf16_f32 v0, v12, v13
	v_cvt_pk_bf16_f32 v1, v14, v15
	v_cvt_pk_bf16_f32 v2, v8, v9
	v_cvt_pk_bf16_f32 v3, v10, v11
	v_cvt_pk_bf16_f32 v4, v4, v5
	v_cvt_pk_bf16_f32 v5, v6, v7
	v_cvt_pk_bf16_f32 v6, v18, v19
	v_cvt_pk_bf16_f32 v7, v22, v23
	global_store_dwordx4 v[16:17], v[0:3], off
	global_store_dwordx4 v[20:21], v[4:7], off offset:256
	s_and_b64 vcc, exec, s[4:5]
	s_mov_b64 s[4:5], -1
	s_cbranch_vccnz .LBB0_526
